# per-batch buffer relocation (KVQ into H(b), attention output into out(b)) so every seam G2..G8 is XCD-local; 7 local barriers with runtime placement check+fallback
# speedup vs baseline: 1.0158x; 1.0158x over previous
.LBB0_944:
	v_ashrrev_i32_e32 v147, 31, v146
	v_lshlrev_b64 v[154:155], 8, v[146:147]
	v_lshl_add_u64 v[184:185], v[136:137], 0, v[154:155]
	global_load_dwordx4 v[154:157], v[184:185], off
	global_load_dwordx4 v[176:179], v[184:185], off offset:16
	global_load_dwordx4 v[180:183], v[184:185], off offset:32
	ds_read_b32 v188, v174
	global_load_dwordx4 v[184:187], v[184:185], off offset:48
	s_cmp_gt_i32 s46, 7
	s_cselect_b64 vcc, -1, 0
	s_and_b64 s[8:9], vcc, exec
	s_waitcnt lgkmcnt(0)
	v_pk_mul_f32 v[222:223], v[112:113], v[188:189] op_sel_hi:[1,0]
	v_pk_mul_f32 v[218:219], v[114:115], v[188:189] op_sel_hi:[1,0]
	v_pk_mul_f32 v[220:221], v[124:125], v[188:189] op_sel_hi:[1,0]
	v_pk_mul_f32 v[200:201], v[222:223], v[222:223]
	v_pk_mul_f32 v[216:217], v[126:127], v[188:189] op_sel_hi:[1,0]
	v_pk_mul_f32 v[198:199], v[218:219], v[218:219]
	v_pk_fma_f32 v[200:201], v[220:221], v[220:221], v[200:201]
	v_pk_mul_f32 v[214:215], v[104:105], v[188:189] op_sel_hi:[1,0]
	v_pk_fma_f32 v[198:199], v[216:217], v[216:217], v[198:199]
	v_add_f32_e32 v147, v200, v201
	v_pk_mul_f32 v[212:213], v[120:121], v[188:189] op_sel_hi:[1,0]
	v_pk_mul_f32 v[190:191], v[214:215], v[214:215]
	v_add_f32_e32 v147, v198, v147
	v_pk_mul_f32 v[210:211], v[106:107], v[188:189] op_sel_hi:[1,0]
	v_pk_fma_f32 v[190:191], v[212:213], v[212:213], v[190:191]
	v_add_f32_e32 v147, v199, v147
	v_pk_mul_f32 v[192:193], v[122:123], v[188:189] op_sel_hi:[1,0]
	v_pk_mul_f32 v[188:189], v[210:211], v[210:211]
	v_add_f32_e32 v147, v190, v147
	v_pk_fma_f32 v[188:189], v[192:193], v[192:193], v[188:189]
	v_add_f32_e32 v147, v191, v147
	v_add_f32_e32 v147, v188, v147
	v_add_f32_e32 v149, v189, v147
	ds_bpermute_b32 v151, v167, v149
	v_cndmask_b32_e32 v147, 1.0, v173, vcc
	s_cselect_b32 s8, 0x100, 0
	v_add_u32_e32 v175, s8, v165
	ds_read_b128 v[188:191], v175
	ds_read_b128 v[198:201], v175 offset:16
	ds_read_b128 v[202:205], v175 offset:128
	ds_read_b128 v[206:209], v175 offset:144
	s_waitcnt lgkmcnt(0)
	v_add_f32_e32 v149, v149, v151
	ds_bpermute_b32 v151, v168, v149
	v_lshl_add_u32 v224, s46, 8, v163
	v_ashrrev_i32_e32 v225, 31, v224
	s_waitcnt lgkmcnt(0)
	v_add_f32_e32 v149, v149, v151
	v_fmamk_f32 v149, v149, 0x3c800000, v172
	v_mul_f32_e32 v151, 0x4b800000, v149
	v_cmp_gt_f32_e32 vcc, s39, v149
	s_nop 1
	v_cndmask_b32_e32 v149, v149, v151, vcc
	v_rsq_f32_e32 v149, v149
	s_nop 0
	v_mul_f32_e32 v151, 0x45800000, v149
	v_cndmask_b32_e32 v149, v149, v151, vcc
	v_mul_f32_e32 v226, v147, v149
	v_pk_mul_f32 v[222:223], v[222:223], v[226:227] op_sel_hi:[1,0]
	v_pk_mul_f32 v[218:219], v[218:219], v[226:227] op_sel_hi:[1,0]
	v_pk_mul_f32 v[212:213], v[212:213], v[226:227] op_sel_hi:[1,0]
	v_pk_mul_f32 v[214:215], v[214:215], v[226:227] op_sel_hi:[1,0]
	v_pk_mul_f32 v[220:221], v[220:221], v[226:227] op_sel_hi:[1,0]
	v_pk_mul_f32 v[216:217], v[216:217], v[226:227] op_sel_hi:[1,0]
	v_pk_mul_f32 v[202:203], v[202:203], v[222:223]
	v_pk_mul_f32 v[204:205], v[204:205], v[218:219]
	v_pk_mul_f32 v[198:199], v[198:199], v[212:213]
	v_pk_mul_f32 v[206:207], v[206:207], v[214:215]
	v_pk_mul_f32 v[188:189], v[188:189], v[220:221]
	v_pk_mul_f32 v[190:191], v[190:191], v[216:217]
	s_waitcnt vmcnt(0)
	v_mov_b32_e32 v212, v154
	v_mov_b32_e32 v213, v156
	v_mov_b32_e32 v156, v155
	v_mov_b32_e32 v154, v176
	v_mov_b32_e32 v155, v178
	v_mov_b32_e32 v178, v177
	v_mov_b32_e32 v177, v182
	v_mov_b32_e32 v182, v181
	v_mov_b32_e32 v176, v180
	v_pk_mul_f32 v[180:181], v[156:157], v[202:203]
	v_pk_mul_f32 v[202:203], v[212:213], v[202:203]
	v_pk_mul_f32 v[214:215], v[178:179], v[204:205]
	v_pk_mul_f32 v[204:205], v[154:155], v[204:205]
	v_pk_mul_f32 v[216:217], v[182:183], v[206:207]
	v_pk_fma_f32 v[180:181], v[212:213], v[188:189], v[180:181] neg_lo:[0,0,1] neg_hi:[0,0,1]
	v_pk_fma_f32 v[156:157], v[156:157], v[188:189], v[202:203]
	v_pk_fma_f32 v[154:155], v[154:155], v[190:191], v[214:215] neg_lo:[0,0,1] neg_hi:[0,0,1]
	v_pk_fma_f32 v[188:189], v[178:179], v[190:191], v[204:205]
	v_pk_fma_f32 v[178:179], v[176:177], v[198:199], v[216:217] neg_lo:[0,0,1] neg_hi:[0,0,1]
	v_pk_mul_f32 v[176:177], v[176:177], v[206:207]
	v_pk_mul_f32 v[190:191], v[210:211], v[226:227] op_sel_hi:[1,0]
	v_pk_fma_f32 v[182:183], v[182:183], v[198:199], v[176:177]
	v_pk_mul_f32 v[176:177], v[192:193], v[226:227] op_sel_hi:[1,0]
	v_pk_mul_f32 v[190:191], v[208:209], v[190:191]
	v_mov_b32_e32 v192, v184
	v_mov_b32_e32 v193, v186
	v_mov_b32_e32 v186, v185
	v_pk_mul_f32 v[176:177], v[200:201], v[176:177]
	v_pk_mul_f32 v[184:185], v[186:187], v[190:191]
	v_pk_mul_f32 v[190:191], v[192:193], v[190:191]
	v_pk_fma_f32 v[184:185], v[192:193], v[176:177], v[184:185] neg_lo:[0,0,1] neg_hi:[0,0,1]
	v_pk_fma_f32 v[186:187], v[186:187], v[176:177], v[190:191]
	v_cvt_pk_bf16_f32 v177, v154, v155
	v_mov_b64_e32 v[154:155], s[96:97]
	s_and_b32 s24, s2, 7
	s_lshl_b32 s24, s24, 22
	s_add_u32 s24, s24, 0x2000000
	v_mov_b32_e32 v236, s24
	v_mov_b32_e32 v237, 0
	v_lshl_add_u64 v[154:155], v[154:155], 0, v[236:237]
	v_cvt_pk_bf16_f32 v176, v180, v181
	v_cvt_pk_bf16_f32 v178, v178, v179
	v_cvt_pk_bf16_f32 v179, v184, v185
	v_cvt_pk_bf16_f32 v180, v156, v157
	v_mad_i64_i32 v[184:185], s[8:9], v146, s40, v[154:155]
	v_lshlrev_b64 v[156:157], 1, v[224:225]
	v_lshl_add_u64 v[184:185], v[184:185], 0, v[156:157]
	v_cvt_pk_bf16_f32 v181, v188, v189
	v_cvt_pk_bf16_f32 v182, v182, v183
	v_cvt_pk_bf16_f32 v183, v186, v187
	global_store_dwordx4 v[184:185], v[176:179], off
	global_store_dwordx4 v[184:185], v[180:183], off offset:64
	v_ashrrev_i32_e32 v153, 31, v152
	v_lshlrev_b64 v[176:177], 8, v[152:153]
	v_lshl_add_u64 v[188:189], v[136:137], 0, v[176:177]
	global_load_dwordx4 v[176:179], v[188:189], off
	global_load_dwordx4 v[180:183], v[188:189], off offset:16
	global_load_dwordx4 v[184:187], v[188:189], off offset:32
	s_nop 0
	global_load_dwordx4 v[188:191], v[188:189], off offset:48
	ds_read_b32 v192, v174 offset:64
	s_waitcnt lgkmcnt(0)
	v_pk_mul_f32 v[214:215], v[110:111], v[192:193] op_sel_hi:[1,0]
	v_pk_mul_f32 v[216:217], v[90:91], v[192:193] op_sel_hi:[1,0]
	v_pk_mul_f32 v[218:219], v[108:109], v[192:193] op_sel_hi:[1,0]
	v_pk_mul_f32 v[220:221], v[88:89], v[192:193] op_sel_hi:[1,0]
	v_pk_mul_f32 v[222:223], v[118:119], v[192:193] op_sel_hi:[1,0]
	v_pk_mul_f32 v[224:225], v[98:99], v[192:193] op_sel_hi:[1,0]
	v_pk_mul_f32 v[226:227], v[116:117], v[192:193] op_sel_hi:[1,0]
	v_pk_mul_f32 v[192:193], v[96:97], v[192:193] op_sel_hi:[1,0]
	v_pk_mul_f32 v[202:203], v[224:225], v[224:225]
	v_pk_mul_f32 v[204:205], v[192:193], v[192:193]
	v_pk_fma_f32 v[202:203], v[222:223], v[222:223], v[202:203]
	v_pk_fma_f32 v[204:205], v[226:227], v[226:227], v[204:205]
	v_pk_mul_f32 v[200:201], v[220:221], v[220:221]
	v_add_f32_e32 v149, v204, v205
	v_add_f32_e32 v149, v202, v149
	v_pk_fma_f32 v[200:201], v[218:219], v[218:219], v[200:201]
	v_add_f32_e32 v149, v203, v149
	v_pk_mul_f32 v[198:199], v[216:217], v[216:217]
	v_add_f32_e32 v149, v200, v149
	v_pk_fma_f32 v[198:199], v[214:215], v[214:215], v[198:199]
	v_add_f32_e32 v149, v201, v149
	v_add_f32_e32 v149, v198, v149
	v_add_f32_e32 v149, v199, v149
	ds_bpermute_b32 v151, v167, v149
	ds_read_b128 v[198:201], v175
	ds_read_b128 v[202:205], v175 offset:16
	ds_read_b128 v[206:209], v175 offset:128
	ds_read_b128 v[210:213], v175 offset:144
	s_waitcnt lgkmcnt(4)
	v_add_f32_e32 v149, v149, v151
	ds_bpermute_b32 v151, v168, v149
	s_waitcnt lgkmcnt(0)
	v_add_f32_e32 v149, v149, v151
	v_fmamk_f32 v149, v149, 0x3c800000, v172
	v_mul_f32_e32 v151, 0x4b800000, v149
	v_cmp_gt_f32_e32 vcc, s39, v149
	s_nop 1
	v_cndmask_b32_e32 v149, v149, v151, vcc
	v_rsq_f32_e32 v149, v149
	s_nop 0
	v_mul_f32_e32 v151, 0x45800000, v149
	v_cndmask_b32_e32 v149, v149, v151, vcc
	v_mul_f32_e32 v228, v147, v149
	v_pk_mul_f32 v[192:193], v[192:193], v[228:229] op_sel_hi:[1,0]
	v_pk_mul_f32 v[224:225], v[224:225], v[228:229] op_sel_hi:[1,0]
	v_pk_mul_f32 v[220:221], v[220:221], v[228:229] op_sel_hi:[1,0]
	v_pk_mul_f32 v[216:217], v[216:217], v[228:229] op_sel_hi:[1,0]
	v_pk_mul_f32 v[226:227], v[226:227], v[228:229] op_sel_hi:[1,0]
	v_pk_mul_f32 v[222:223], v[222:223], v[228:229] op_sel_hi:[1,0]
	v_pk_mul_f32 v[214:215], v[214:215], v[228:229] op_sel_hi:[1,0]
	v_pk_mul_f32 v[192:193], v[206:207], v[192:193]
	v_pk_mul_f32 v[206:207], v[208:209], v[224:225]
	v_pk_mul_f32 v[208:209], v[210:211], v[220:221]
	v_pk_mul_f32 v[210:211], v[212:213], v[216:217]
	v_pk_mul_f32 v[198:199], v[198:199], v[226:227]
	v_pk_mul_f32 v[200:201], v[200:201], v[222:223]
	v_pk_mul_f32 v[204:205], v[204:205], v[214:215]
	v_pk_mul_f32 v[218:219], v[218:219], v[228:229] op_sel_hi:[1,0]
	s_waitcnt vmcnt(3)
	v_mov_b32_e32 v212, v176
	v_mov_b32_e32 v213, v178
	v_mov_b32_e32 v178, v177
	s_waitcnt vmcnt(2)
	v_mov_b32_e32 v177, v182
	v_mov_b32_e32 v182, v181
	v_mov_b32_e32 v176, v180
	s_waitcnt vmcnt(1)
	v_mov_b32_e32 v181, v186
	v_mov_b32_e32 v186, v185
	s_waitcnt vmcnt(0)
	v_mov_b32_e32 v185, v190
	v_pk_mul_f32 v[214:215], v[178:179], v[192:193]
	v_pk_mul_f32 v[192:193], v[212:213], v[192:193]
	v_pk_mul_f32 v[216:217], v[182:183], v[206:207]
	v_mov_b32_e32 v190, v189
	v_mov_b32_e32 v180, v184
	v_mov_b32_e32 v184, v188
	v_pk_mul_f32 v[206:207], v[176:177], v[206:207]
	v_pk_fma_f32 v[192:193], v[178:179], v[198:199], v[192:193]
	v_pk_fma_f32 v[178:179], v[176:177], v[200:201], v[216:217] neg_lo:[0,0,1] neg_hi:[0,0,1]
	v_pk_mul_f32 v[176:177], v[190:191], v[210:211]
	v_pk_mul_f32 v[202:203], v[202:203], v[218:219]
	v_pk_mul_f32 v[218:219], v[186:187], v[208:209]
	v_pk_fma_f32 v[188:189], v[184:185], v[204:205], v[176:177] neg_lo:[0,0,1] neg_hi:[0,0,1]
	v_pk_mul_f32 v[176:177], v[184:185], v[210:211]
	v_pk_mul_f32 v[208:209], v[180:181], v[208:209]
	v_pk_fma_f32 v[182:183], v[182:183], v[200:201], v[206:207]
	v_pk_fma_f32 v[180:181], v[180:181], v[202:203], v[218:219] neg_lo:[0,0,1] neg_hi:[0,0,1]
	v_pk_fma_f32 v[184:185], v[190:191], v[204:205], v[176:177]
	v_pk_fma_f32 v[212:213], v[212:213], v[198:199], v[214:215] neg_lo:[0,0,1] neg_hi:[0,0,1]
	v_cvt_pk_bf16_f32 v177, v178, v179
	v_cvt_pk_bf16_f32 v178, v180, v181
	v_cvt_pk_bf16_f32 v181, v182, v183
	v_cvt_pk_bf16_f32 v183, v184, v185
	v_mad_i64_i32 v[184:185], s[8:9], v152, s40, v[154:155]
	v_pk_fma_f32 v[186:187], v[186:187], v[202:203], v[208:209]
	v_cvt_pk_bf16_f32 v176, v212, v213
	v_cvt_pk_bf16_f32 v179, v188, v189
	v_lshl_add_u64 v[184:185], v[184:185], 0, v[156:157]
	v_cvt_pk_bf16_f32 v180, v192, v193
	v_cvt_pk_bf16_f32 v182, v186, v187
	global_store_dwordx4 v[184:185], v[176:179], off
	global_store_dwordx4 v[184:185], v[180:183], off offset:64
	v_ashrrev_i32_e32 v151, 31, v150
	v_lshlrev_b64 v[176:177], 8, v[150:151]
	v_lshl_add_u64 v[188:189], v[136:137], 0, v[176:177]
	global_load_dwordx4 v[176:179], v[188:189], off
	global_load_dwordx4 v[180:183], v[188:189], off offset:16
	global_load_dwordx4 v[184:187], v[188:189], off offset:32
	s_nop 0
	global_load_dwordx4 v[188:191], v[188:189], off offset:48
	ds_read_b32 v192, v174 offset:128
	s_waitcnt lgkmcnt(0)
	v_pk_mul_f32 v[214:215], v[94:95], v[192:193] op_sel_hi:[1,0]
	v_pk_mul_f32 v[216:217], v[74:75], v[192:193] op_sel_hi:[1,0]
	v_pk_mul_f32 v[218:219], v[92:93], v[192:193] op_sel_hi:[1,0]
	v_pk_mul_f32 v[220:221], v[72:73], v[192:193] op_sel_hi:[1,0]
	v_pk_mul_f32 v[222:223], v[102:103], v[192:193] op_sel_hi:[1,0]
	v_pk_mul_f32 v[224:225], v[82:83], v[192:193] op_sel_hi:[1,0]
	v_pk_mul_f32 v[226:227], v[100:101], v[192:193] op_sel_hi:[1,0]
	v_pk_mul_f32 v[192:193], v[80:81], v[192:193] op_sel_hi:[1,0]
	v_pk_mul_f32 v[202:203], v[224:225], v[224:225]
	v_pk_mul_f32 v[204:205], v[192:193], v[192:193]
	v_pk_fma_f32 v[202:203], v[222:223], v[222:223], v[202:203]
	v_pk_fma_f32 v[204:205], v[226:227], v[226:227], v[204:205]
	v_pk_mul_f32 v[200:201], v[220:221], v[220:221]
	v_add_f32_e32 v149, v204, v205
	v_add_f32_e32 v149, v202, v149
	v_pk_fma_f32 v[200:201], v[218:219], v[218:219], v[200:201]
	v_add_f32_e32 v149, v203, v149
	v_pk_mul_f32 v[198:199], v[216:217], v[216:217]
	v_add_f32_e32 v149, v200, v149
	v_pk_fma_f32 v[198:199], v[214:215], v[214:215], v[198:199]
	v_add_f32_e32 v149, v201, v149
	v_add_f32_e32 v149, v198, v149
	v_add_f32_e32 v149, v199, v149
	ds_bpermute_b32 v151, v167, v149
	ds_read_b128 v[198:201], v175
	ds_read_b128 v[202:205], v175 offset:16
	ds_read_b128 v[206:209], v175 offset:128
	ds_read_b128 v[210:213], v175 offset:144
	s_waitcnt lgkmcnt(4)
	v_add_f32_e32 v149, v149, v151
	ds_bpermute_b32 v151, v168, v149
	s_waitcnt lgkmcnt(0)
	v_add_f32_e32 v149, v149, v151
	v_fmamk_f32 v149, v149, 0x3c800000, v172
	v_mul_f32_e32 v151, 0x4b800000, v149
	v_cmp_gt_f32_e32 vcc, s39, v149
	s_nop 1
	v_cndmask_b32_e32 v149, v149, v151, vcc
	v_rsq_f32_e32 v149, v149
	s_nop 0
	v_mul_f32_e32 v151, 0x45800000, v149
	v_cndmask_b32_e32 v149, v149, v151, vcc
	v_mul_f32_e32 v228, v147, v149
	v_pk_mul_f32 v[192:193], v[192:193], v[228:229] op_sel_hi:[1,0]
	v_pk_mul_f32 v[224:225], v[224:225], v[228:229] op_sel_hi:[1,0]
	v_pk_mul_f32 v[220:221], v[220:221], v[228:229] op_sel_hi:[1,0]
	v_pk_mul_f32 v[216:217], v[216:217], v[228:229] op_sel_hi:[1,0]
	v_pk_mul_f32 v[226:227], v[226:227], v[228:229] op_sel_hi:[1,0]
	v_pk_mul_f32 v[222:223], v[222:223], v[228:229] op_sel_hi:[1,0]
	v_pk_mul_f32 v[214:215], v[214:215], v[228:229] op_sel_hi:[1,0]
	v_pk_mul_f32 v[192:193], v[206:207], v[192:193]
	v_pk_mul_f32 v[206:207], v[208:209], v[224:225]
	v_pk_mul_f32 v[208:209], v[210:211], v[220:221]
	v_pk_mul_f32 v[210:211], v[212:213], v[216:217]
	v_pk_mul_f32 v[198:199], v[198:199], v[226:227]
	v_pk_mul_f32 v[200:201], v[200:201], v[222:223]
	v_pk_mul_f32 v[204:205], v[204:205], v[214:215]
	v_pk_mul_f32 v[218:219], v[218:219], v[228:229] op_sel_hi:[1,0]
	s_waitcnt vmcnt(3)
	v_mov_b32_e32 v212, v176
	v_mov_b32_e32 v213, v178
	v_mov_b32_e32 v178, v177
	s_waitcnt vmcnt(2)
	v_mov_b32_e32 v177, v182
	v_mov_b32_e32 v182, v181
	v_mov_b32_e32 v176, v180
	s_waitcnt vmcnt(1)
	v_mov_b32_e32 v181, v186
	v_mov_b32_e32 v186, v185
	s_waitcnt vmcnt(0)
	v_mov_b32_e32 v185, v190
	v_pk_mul_f32 v[214:215], v[178:179], v[192:193]
	v_pk_mul_f32 v[192:193], v[212:213], v[192:193]
	v_pk_mul_f32 v[216:217], v[182:183], v[206:207]
	v_mov_b32_e32 v190, v189
	v_mov_b32_e32 v180, v184
	v_mov_b32_e32 v184, v188
	v_pk_mul_f32 v[206:207], v[176:177], v[206:207]
	v_pk_fma_f32 v[192:193], v[178:179], v[198:199], v[192:193]
	v_pk_fma_f32 v[178:179], v[176:177], v[200:201], v[216:217] neg_lo:[0,0,1] neg_hi:[0,0,1]
	v_pk_mul_f32 v[176:177], v[190:191], v[210:211]
	v_pk_mul_f32 v[202:203], v[202:203], v[218:219]
	v_pk_mul_f32 v[218:219], v[186:187], v[208:209]
	v_pk_fma_f32 v[188:189], v[184:185], v[204:205], v[176:177] neg_lo:[0,0,1] neg_hi:[0,0,1]
	v_pk_mul_f32 v[176:177], v[184:185], v[210:211]
	v_pk_mul_f32 v[208:209], v[180:181], v[208:209]
	v_pk_fma_f32 v[182:183], v[182:183], v[200:201], v[206:207]
	v_pk_fma_f32 v[180:181], v[180:181], v[202:203], v[218:219] neg_lo:[0,0,1] neg_hi:[0,0,1]
	v_pk_fma_f32 v[184:185], v[190:191], v[204:205], v[176:177]
	v_pk_fma_f32 v[212:213], v[212:213], v[198:199], v[214:215] neg_lo:[0,0,1] neg_hi:[0,0,1]
	v_cvt_pk_bf16_f32 v177, v178, v179
	v_cvt_pk_bf16_f32 v178, v180, v181
	v_cvt_pk_bf16_f32 v181, v182, v183
	v_cvt_pk_bf16_f32 v183, v184, v185
	v_mad_i64_i32 v[184:185], s[8:9], v150, s40, v[154:155]
	v_pk_fma_f32 v[186:187], v[186:187], v[202:203], v[208:209]
	v_cvt_pk_bf16_f32 v176, v212, v213
	v_cvt_pk_bf16_f32 v179, v188, v189
	v_lshl_add_u64 v[184:185], v[184:185], 0, v[156:157]
	v_cvt_pk_bf16_f32 v180, v192, v193
	v_cvt_pk_bf16_f32 v182, v186, v187
	global_store_dwordx4 v[184:185], v[176:179], off
	global_store_dwordx4 v[184:185], v[180:183], off offset:64
	v_ashrrev_i32_e32 v149, 31, v148
	v_lshlrev_b64 v[176:177], 8, v[148:149]
	v_lshl_add_u64 v[188:189], v[136:137], 0, v[176:177]
	global_load_dwordx4 v[176:179], v[188:189], off
	global_load_dwordx4 v[180:183], v[188:189], off offset:16
	global_load_dwordx4 v[184:187], v[188:189], off offset:32
	s_nop 0
	global_load_dwordx4 v[188:191], v[188:189], off offset:48
	ds_read_b32 v192, v174 offset:192
	s_waitcnt lgkmcnt(0)
	v_pk_mul_f32 v[214:215], v[78:79], v[192:193] op_sel_hi:[1,0]
	v_pk_mul_f32 v[216:217], v[66:67], v[192:193] op_sel_hi:[1,0]
	v_pk_mul_f32 v[218:219], v[76:77], v[192:193] op_sel_hi:[1,0]
	v_pk_mul_f32 v[220:221], v[64:65], v[192:193] op_sel_hi:[1,0]
	v_pk_mul_f32 v[222:223], v[86:87], v[192:193] op_sel_hi:[1,0]
	v_pk_mul_f32 v[224:225], v[70:71], v[192:193] op_sel_hi:[1,0]
	v_pk_mul_f32 v[226:227], v[84:85], v[192:193] op_sel_hi:[1,0]
	v_pk_mul_f32 v[192:193], v[68:69], v[192:193] op_sel_hi:[1,0]
	v_pk_mul_f32 v[202:203], v[224:225], v[224:225]
	v_pk_mul_f32 v[204:205], v[192:193], v[192:193]
	v_pk_fma_f32 v[202:203], v[222:223], v[222:223], v[202:203]
	v_pk_fma_f32 v[204:205], v[226:227], v[226:227], v[204:205]
	v_pk_mul_f32 v[200:201], v[220:221], v[220:221]
	v_add_f32_e32 v149, v204, v205
	v_add_f32_e32 v149, v202, v149
	v_pk_fma_f32 v[200:201], v[218:219], v[218:219], v[200:201]
	v_add_f32_e32 v149, v203, v149
	v_pk_mul_f32 v[198:199], v[216:217], v[216:217]
	v_add_f32_e32 v149, v200, v149
	v_pk_fma_f32 v[198:199], v[214:215], v[214:215], v[198:199]
	v_add_f32_e32 v149, v201, v149
	v_add_f32_e32 v149, v198, v149
	v_add_f32_e32 v149, v199, v149
	ds_bpermute_b32 v151, v167, v149
	ds_read_b128 v[198:201], v175
	ds_read_b128 v[202:205], v175 offset:16
	ds_read_b128 v[206:209], v175 offset:128
	ds_read_b128 v[210:213], v175 offset:144
	s_waitcnt lgkmcnt(4)
	v_add_f32_e32 v149, v149, v151
	ds_bpermute_b32 v151, v168, v149
	s_waitcnt lgkmcnt(0)
	v_add_f32_e32 v149, v149, v151
	v_fmamk_f32 v149, v149, 0x3c800000, v172
	v_mul_f32_e32 v151, 0x4b800000, v149
	v_cmp_gt_f32_e32 vcc, s39, v149
	s_nop 1
	v_cndmask_b32_e32 v149, v149, v151, vcc
	v_rsq_f32_e32 v149, v149
	s_nop 0
	v_mul_f32_e32 v151, 0x45800000, v149
	v_cndmask_b32_e32 v149, v149, v151, vcc
	v_mul_f32_e32 v228, v147, v149
	v_pk_mul_f32 v[192:193], v[192:193], v[228:229] op_sel_hi:[1,0]
	v_pk_mul_f32 v[224:225], v[224:225], v[228:229] op_sel_hi:[1,0]
	v_pk_mul_f32 v[220:221], v[220:221], v[228:229] op_sel_hi:[1,0]
	v_pk_mul_f32 v[216:217], v[216:217], v[228:229] op_sel_hi:[1,0]
	v_pk_mul_f32 v[226:227], v[226:227], v[228:229] op_sel_hi:[1,0]
	v_pk_mul_f32 v[222:223], v[222:223], v[228:229] op_sel_hi:[1,0]
	v_pk_mul_f32 v[214:215], v[214:215], v[228:229] op_sel_hi:[1,0]
	v_pk_mul_f32 v[192:193], v[206:207], v[192:193]
	v_pk_mul_f32 v[206:207], v[208:209], v[224:225]
	v_pk_mul_f32 v[208:209], v[210:211], v[220:221]
	v_pk_mul_f32 v[210:211], v[212:213], v[216:217]
	v_pk_mul_f32 v[198:199], v[198:199], v[226:227]
	v_pk_mul_f32 v[200:201], v[200:201], v[222:223]
	v_pk_mul_f32 v[204:205], v[204:205], v[214:215]
	v_pk_mul_f32 v[218:219], v[218:219], v[228:229] op_sel_hi:[1,0]
	s_waitcnt vmcnt(3)
	v_mov_b32_e32 v212, v176
	v_mov_b32_e32 v213, v178
	v_mov_b32_e32 v178, v177
	s_waitcnt vmcnt(2)
	v_mov_b32_e32 v177, v182
	v_mov_b32_e32 v182, v181
	v_mov_b32_e32 v176, v180
	s_waitcnt vmcnt(1)
	v_mov_b32_e32 v181, v186
	v_mov_b32_e32 v186, v185
	s_waitcnt vmcnt(0)
	v_mov_b32_e32 v185, v190
	v_pk_mul_f32 v[214:215], v[178:179], v[192:193]
	v_pk_mul_f32 v[192:193], v[212:213], v[192:193]
	v_pk_mul_f32 v[216:217], v[182:183], v[206:207]
	v_mov_b32_e32 v190, v189
	v_mov_b32_e32 v180, v184
	v_mov_b32_e32 v184, v188
	v_pk_mul_f32 v[206:207], v[176:177], v[206:207]
	v_pk_fma_f32 v[192:193], v[178:179], v[198:199], v[192:193]
	v_pk_fma_f32 v[178:179], v[176:177], v[200:201], v[216:217] neg_lo:[0,0,1] neg_hi:[0,0,1]
	v_pk_mul_f32 v[176:177], v[190:191], v[210:211]
	v_pk_mul_f32 v[202:203], v[202:203], v[218:219]
	v_pk_mul_f32 v[218:219], v[186:187], v[208:209]
	v_pk_fma_f32 v[188:189], v[184:185], v[204:205], v[176:177] neg_lo:[0,0,1] neg_hi:[0,0,1]
	v_pk_mul_f32 v[176:177], v[184:185], v[210:211]
	v_pk_mul_f32 v[208:209], v[180:181], v[208:209]
	v_pk_fma_f32 v[182:183], v[182:183], v[200:201], v[206:207]
	v_pk_fma_f32 v[180:181], v[180:181], v[202:203], v[218:219] neg_lo:[0,0,1] neg_hi:[0,0,1]
	v_pk_fma_f32 v[184:185], v[190:191], v[204:205], v[176:177]
	v_pk_fma_f32 v[212:213], v[212:213], v[198:199], v[214:215] neg_lo:[0,0,1] neg_hi:[0,0,1]
	v_cvt_pk_bf16_f32 v177, v178, v179
	v_cvt_pk_bf16_f32 v178, v180, v181
	v_cvt_pk_bf16_f32 v181, v182, v183
	v_cvt_pk_bf16_f32 v183, v184, v185
	v_mad_i64_i32 v[184:185], s[8:9], v148, s40, v[154:155]
	v_pk_fma_f32 v[186:187], v[186:187], v[202:203], v[208:209]
	v_cvt_pk_bf16_f32 v176, v212, v213
	v_cvt_pk_bf16_f32 v179, v188, v189
	v_lshl_add_u64 v[184:185], v[184:185], 0, v[156:157]
	v_cvt_pk_bf16_f32 v180, v192, v193
	v_cvt_pk_bf16_f32 v182, v186, v187
	global_store_dwordx4 v[184:185], v[176:179], off
	global_store_dwordx4 v[184:185], v[180:183], off offset:64
	v_add_u32_e32 v192, 0x80, v146
	v_ashrrev_i32_e32 v193, 31, v192
	v_lshlrev_b64 v[176:177], 8, v[192:193]
	v_lshl_add_u64 v[188:189], v[136:137], 0, v[176:177]
	global_load_dwordx4 v[176:179], v[188:189], off
	global_load_dwordx4 v[180:183], v[188:189], off offset:16
	global_load_dwordx4 v[184:187], v[188:189], off offset:32
	s_nop 0
	global_load_dwordx4 v[188:191], v[188:189], off offset:48
	ds_read_b32 v198, v174 offset:512
	s_waitcnt lgkmcnt(0)
	v_pk_mul_f32 v[228:229], v[48:49], v[198:199] op_sel_hi:[1,0]
	v_pk_mul_f32 v[224:225], v[50:51], v[198:199] op_sel_hi:[1,0]
	v_pk_mul_f32 v[226:227], v[60:61], v[198:199] op_sel_hi:[1,0]
	v_pk_mul_f32 v[204:205], v[228:229], v[228:229]
	v_pk_mul_f32 v[222:223], v[62:63], v[198:199] op_sel_hi:[1,0]
	v_pk_mul_f32 v[202:203], v[224:225], v[224:225]
	v_pk_fma_f32 v[204:205], v[226:227], v[226:227], v[204:205]
	v_pk_mul_f32 v[220:221], v[40:41], v[198:199] op_sel_hi:[1,0]
	v_pk_fma_f32 v[202:203], v[222:223], v[222:223], v[202:203]
	v_add_f32_e32 v149, v204, v205
	v_pk_mul_f32 v[218:219], v[56:57], v[198:199] op_sel_hi:[1,0]
	v_pk_mul_f32 v[200:201], v[220:221], v[220:221]
	v_add_f32_e32 v149, v202, v149
	v_pk_mul_f32 v[216:217], v[42:43], v[198:199] op_sel_hi:[1,0]
	v_pk_fma_f32 v[200:201], v[218:219], v[218:219], v[200:201]
	v_add_f32_e32 v149, v203, v149
	v_pk_mul_f32 v[214:215], v[58:59], v[198:199] op_sel_hi:[1,0]
	v_pk_mul_f32 v[198:199], v[216:217], v[216:217]
	v_add_f32_e32 v149, v200, v149
	v_pk_fma_f32 v[198:199], v[214:215], v[214:215], v[198:199]
	v_add_f32_e32 v149, v201, v149
	v_add_f32_e32 v149, v198, v149
	v_add_f32_e32 v149, v199, v149
	ds_bpermute_b32 v151, v167, v149
	ds_read_b128 v[198:201], v175
	ds_read_b128 v[202:205], v175 offset:16
	ds_read_b128 v[206:209], v175 offset:128
	ds_read_b128 v[210:213], v175 offset:144
	s_waitcnt lgkmcnt(4)
	v_add_f32_e32 v149, v149, v151
	ds_bpermute_b32 v151, v168, v149
	s_waitcnt lgkmcnt(0)
	v_add_f32_e32 v149, v149, v151
	v_fmamk_f32 v149, v149, 0x3c800000, v172
	v_mul_f32_e32 v151, 0x4b800000, v149
	v_cmp_gt_f32_e32 vcc, s39, v149
	s_nop 1
	v_cndmask_b32_e32 v149, v149, v151, vcc
	v_rsq_f32_e32 v149, v149
	s_nop 0
	v_mul_f32_e32 v151, 0x45800000, v149
	v_cndmask_b32_e32 v149, v149, v151, vcc
	v_mul_f32_e32 v230, v147, v149
	v_pk_mul_f32 v[228:229], v[228:229], v[230:231] op_sel_hi:[1,0]
	v_pk_mul_f32 v[224:225], v[224:225], v[230:231] op_sel_hi:[1,0]
	v_pk_mul_f32 v[214:215], v[214:215], v[230:231] op_sel_hi:[1,0]
	v_pk_mul_f32 v[226:227], v[226:227], v[230:231] op_sel_hi:[1,0]
	v_pk_mul_f32 v[222:223], v[222:223], v[230:231] op_sel_hi:[1,0]
	v_pk_mul_f32 v[218:219], v[218:219], v[230:231] op_sel_hi:[1,0]
	v_pk_mul_f32 v[216:217], v[216:217], v[230:231] op_sel_hi:[1,0]
	v_pk_mul_f32 v[206:207], v[206:207], v[228:229]
	v_pk_mul_f32 v[208:209], v[208:209], v[224:225]
	v_pk_mul_f32 v[204:205], v[204:205], v[214:215]
	v_pk_mul_f32 v[220:221], v[220:221], v[230:231] op_sel_hi:[1,0]
	v_pk_mul_f32 v[198:199], v[198:199], v[226:227]
	v_pk_mul_f32 v[200:201], v[200:201], v[222:223]
	v_pk_mul_f32 v[202:203], v[202:203], v[218:219]
	v_pk_mul_f32 v[212:213], v[212:213], v[216:217]
	v_pk_mul_f32 v[210:211], v[210:211], v[220:221]
	s_waitcnt vmcnt(3)
	v_mov_b32_e32 v214, v176
	v_mov_b32_e32 v215, v178
	v_mov_b32_e32 v178, v177
	s_waitcnt vmcnt(2)
	v_mov_b32_e32 v177, v182
	v_mov_b32_e32 v182, v181
	v_mov_b32_e32 v176, v180
	s_waitcnt vmcnt(1)
	v_mov_b32_e32 v181, v186
	v_mov_b32_e32 v186, v185
	s_waitcnt vmcnt(0)
	v_mov_b32_e32 v185, v190
	v_pk_mul_f32 v[216:217], v[178:179], v[206:207]
	v_pk_mul_f32 v[206:207], v[214:215], v[206:207]
	v_pk_mul_f32 v[218:219], v[182:183], v[208:209]
	v_mov_b32_e32 v190, v189
	v_mov_b32_e32 v180, v184
	v_mov_b32_e32 v184, v188
	v_pk_mul_f32 v[208:209], v[176:177], v[208:209]
	v_pk_fma_f32 v[214:215], v[214:215], v[198:199], v[216:217] neg_lo:[0,0,1] neg_hi:[0,0,1]
	v_pk_fma_f32 v[198:199], v[178:179], v[198:199], v[206:207]
	v_pk_fma_f32 v[178:179], v[176:177], v[200:201], v[218:219] neg_lo:[0,0,1] neg_hi:[0,0,1]
	v_pk_mul_f32 v[176:177], v[190:191], v[212:213]
	v_pk_mul_f32 v[220:221], v[186:187], v[210:211]
	v_pk_fma_f32 v[188:189], v[184:185], v[204:205], v[176:177] neg_lo:[0,0,1] neg_hi:[0,0,1]
	v_pk_mul_f32 v[176:177], v[184:185], v[212:213]
	v_pk_mul_f32 v[210:211], v[180:181], v[210:211]
	v_pk_fma_f32 v[182:183], v[182:183], v[200:201], v[208:209]
	v_pk_fma_f32 v[180:181], v[180:181], v[202:203], v[220:221] neg_lo:[0,0,1] neg_hi:[0,0,1]
	v_pk_fma_f32 v[184:185], v[190:191], v[204:205], v[176:177]
	v_cvt_pk_bf16_f32 v177, v178, v179
	v_cvt_pk_bf16_f32 v178, v180, v181
	v_cvt_pk_bf16_f32 v181, v182, v183
	v_cvt_pk_bf16_f32 v183, v184, v185
	v_mad_i64_i32 v[184:185], s[8:9], v192, s40, v[154:155]
	v_pk_fma_f32 v[186:187], v[186:187], v[202:203], v[210:211]
	v_cvt_pk_bf16_f32 v176, v214, v215
	v_cvt_pk_bf16_f32 v179, v188, v189
	v_lshl_add_u64 v[184:185], v[184:185], 0, v[156:157]
	v_cvt_pk_bf16_f32 v180, v198, v199
	v_cvt_pk_bf16_f32 v182, v186, v187
	global_store_dwordx4 v[184:185], v[176:179], off
	global_store_dwordx4 v[184:185], v[180:183], off offset:64
	v_add_u32_e32 v192, 0x90, v146
	v_ashrrev_i32_e32 v193, 31, v192
	v_lshlrev_b64 v[176:177], 8, v[192:193]
	v_lshl_add_u64 v[188:189], v[136:137], 0, v[176:177]
	global_load_dwordx4 v[176:179], v[188:189], off
	global_load_dwordx4 v[180:183], v[188:189], off offset:16
	global_load_dwordx4 v[184:187], v[188:189], off offset:32
	s_nop 0
	global_load_dwordx4 v[188:191], v[188:189], off offset:48
	ds_read_b32 v198, v174 offset:576
	s_waitcnt lgkmcnt(0)
	v_pk_mul_f32 v[228:229], v[36:37], v[198:199] op_sel_hi:[1,0]
	v_pk_mul_f32 v[224:225], v[38:39], v[198:199] op_sel_hi:[1,0]
	v_pk_mul_f32 v[226:227], v[52:53], v[198:199] op_sel_hi:[1,0]
	v_pk_mul_f32 v[204:205], v[228:229], v[228:229]
	v_pk_mul_f32 v[222:223], v[54:55], v[198:199] op_sel_hi:[1,0]
	v_pk_mul_f32 v[202:203], v[224:225], v[224:225]
	v_pk_fma_f32 v[204:205], v[226:227], v[226:227], v[204:205]
	v_pk_mul_f32 v[220:221], v[28:29], v[198:199] op_sel_hi:[1,0]
	v_pk_fma_f32 v[202:203], v[222:223], v[222:223], v[202:203]
	v_add_f32_e32 v149, v204, v205
	v_pk_mul_f32 v[218:219], v[44:45], v[198:199] op_sel_hi:[1,0]
	v_pk_mul_f32 v[200:201], v[220:221], v[220:221]
	v_add_f32_e32 v149, v202, v149
	v_pk_mul_f32 v[216:217], v[30:31], v[198:199] op_sel_hi:[1,0]
	v_pk_fma_f32 v[200:201], v[218:219], v[218:219], v[200:201]
	v_add_f32_e32 v149, v203, v149
	v_pk_mul_f32 v[214:215], v[46:47], v[198:199] op_sel_hi:[1,0]
	v_pk_mul_f32 v[198:199], v[216:217], v[216:217]
	v_add_f32_e32 v149, v200, v149
	v_pk_fma_f32 v[198:199], v[214:215], v[214:215], v[198:199]
	v_add_f32_e32 v149, v201, v149
	v_add_f32_e32 v149, v198, v149
	v_add_f32_e32 v149, v199, v149
	ds_bpermute_b32 v151, v167, v149
	ds_read_b128 v[198:201], v175
	ds_read_b128 v[202:205], v175 offset:16
	ds_read_b128 v[206:209], v175 offset:128
	ds_read_b128 v[210:213], v175 offset:144
	s_waitcnt lgkmcnt(4)
	v_add_f32_e32 v149, v149, v151
	ds_bpermute_b32 v151, v168, v149
	s_waitcnt lgkmcnt(0)
	v_add_f32_e32 v149, v149, v151
	v_fmamk_f32 v149, v149, 0x3c800000, v172
	v_mul_f32_e32 v151, 0x4b800000, v149
	v_cmp_gt_f32_e32 vcc, s39, v149
	s_nop 1
	v_cndmask_b32_e32 v149, v149, v151, vcc
	v_rsq_f32_e32 v149, v149
	s_nop 0
	v_mul_f32_e32 v151, 0x45800000, v149
	v_cndmask_b32_e32 v149, v149, v151, vcc
	v_mul_f32_e32 v230, v147, v149
	v_pk_mul_f32 v[228:229], v[228:229], v[230:231] op_sel_hi:[1,0]
	v_pk_mul_f32 v[224:225], v[224:225], v[230:231] op_sel_hi:[1,0]
	v_pk_mul_f32 v[214:215], v[214:215], v[230:231] op_sel_hi:[1,0]
	v_pk_mul_f32 v[226:227], v[226:227], v[230:231] op_sel_hi:[1,0]
	v_pk_mul_f32 v[222:223], v[222:223], v[230:231] op_sel_hi:[1,0]
	v_pk_mul_f32 v[218:219], v[218:219], v[230:231] op_sel_hi:[1,0]
	v_pk_mul_f32 v[216:217], v[216:217], v[230:231] op_sel_hi:[1,0]
	v_pk_mul_f32 v[206:207], v[206:207], v[228:229]
	v_pk_mul_f32 v[208:209], v[208:209], v[224:225]
	v_pk_mul_f32 v[204:205], v[204:205], v[214:215]
	v_pk_mul_f32 v[220:221], v[220:221], v[230:231] op_sel_hi:[1,0]
	v_pk_mul_f32 v[198:199], v[198:199], v[226:227]
	v_pk_mul_f32 v[200:201], v[200:201], v[222:223]
	v_pk_mul_f32 v[202:203], v[202:203], v[218:219]
	v_pk_mul_f32 v[212:213], v[212:213], v[216:217]
	v_pk_mul_f32 v[210:211], v[210:211], v[220:221]
	s_waitcnt vmcnt(3)
	v_mov_b32_e32 v214, v176
	v_mov_b32_e32 v215, v178
	v_mov_b32_e32 v178, v177
	s_waitcnt vmcnt(2)
	v_mov_b32_e32 v177, v182
	v_mov_b32_e32 v182, v181
	v_mov_b32_e32 v176, v180
	s_waitcnt vmcnt(1)
	v_mov_b32_e32 v181, v186
	v_mov_b32_e32 v186, v185
	s_waitcnt vmcnt(0)
	v_mov_b32_e32 v185, v190
	v_pk_mul_f32 v[216:217], v[178:179], v[206:207]
	v_pk_mul_f32 v[206:207], v[214:215], v[206:207]
	v_pk_mul_f32 v[218:219], v[182:183], v[208:209]
	v_mov_b32_e32 v190, v189
	v_mov_b32_e32 v180, v184
	v_mov_b32_e32 v184, v188
	v_pk_mul_f32 v[208:209], v[176:177], v[208:209]
	v_pk_fma_f32 v[214:215], v[214:215], v[198:199], v[216:217] neg_lo:[0,0,1] neg_hi:[0,0,1]
	v_pk_fma_f32 v[198:199], v[178:179], v[198:199], v[206:207]
	v_pk_fma_f32 v[178:179], v[176:177], v[200:201], v[218:219] neg_lo:[0,0,1] neg_hi:[0,0,1]
	v_pk_mul_f32 v[176:177], v[190:191], v[212:213]
	v_pk_mul_f32 v[220:221], v[186:187], v[210:211]
	v_pk_fma_f32 v[188:189], v[184:185], v[204:205], v[176:177] neg_lo:[0,0,1] neg_hi:[0,0,1]
	v_pk_mul_f32 v[176:177], v[184:185], v[212:213]
	v_pk_mul_f32 v[210:211], v[180:181], v[210:211]
	v_pk_fma_f32 v[182:183], v[182:183], v[200:201], v[208:209]
	v_pk_fma_f32 v[180:181], v[180:181], v[202:203], v[220:221] neg_lo:[0,0,1] neg_hi:[0,0,1]
	v_pk_fma_f32 v[184:185], v[190:191], v[204:205], v[176:177]
	v_cvt_pk_bf16_f32 v177, v178, v179
	v_cvt_pk_bf16_f32 v178, v180, v181
	v_cvt_pk_bf16_f32 v181, v182, v183
	v_cvt_pk_bf16_f32 v183, v184, v185
	v_mad_i64_i32 v[184:185], s[8:9], v192, s40, v[154:155]
	v_pk_fma_f32 v[186:187], v[186:187], v[202:203], v[210:211]
	v_cvt_pk_bf16_f32 v176, v214, v215
	v_cvt_pk_bf16_f32 v179, v188, v189
	v_lshl_add_u64 v[184:185], v[184:185], 0, v[156:157]
	v_cvt_pk_bf16_f32 v180, v198, v199
	v_cvt_pk_bf16_f32 v182, v186, v187
	global_store_dwordx4 v[184:185], v[176:179], off
	global_store_dwordx4 v[184:185], v[180:183], off offset:64
	v_add_u32_e32 v192, 0xa0, v146
	v_ashrrev_i32_e32 v193, 31, v192
	v_lshlrev_b64 v[176:177], 8, v[192:193]
	v_lshl_add_u64 v[188:189], v[136:137], 0, v[176:177]
	global_load_dwordx4 v[176:179], v[188:189], off
	global_load_dwordx4 v[180:183], v[188:189], off offset:16
	global_load_dwordx4 v[184:187], v[188:189], off offset:32
	s_nop 0
	global_load_dwordx4 v[188:191], v[188:189], off offset:48
	ds_read_b32 v198, v174 offset:640
	s_waitcnt lgkmcnt(0)
	v_pk_mul_f32 v[228:229], v[16:17], v[198:199] op_sel_hi:[1,0]
	v_pk_mul_f32 v[224:225], v[18:19], v[198:199] op_sel_hi:[1,0]
	v_pk_mul_f32 v[226:227], v[32:33], v[198:199] op_sel_hi:[1,0]
	v_pk_mul_f32 v[204:205], v[228:229], v[228:229]
	v_pk_mul_f32 v[222:223], v[34:35], v[198:199] op_sel_hi:[1,0]
	v_pk_mul_f32 v[202:203], v[224:225], v[224:225]
	v_pk_fma_f32 v[204:205], v[226:227], v[226:227], v[204:205]
	v_pk_mul_f32 v[220:221], v[8:9], v[198:199] op_sel_hi:[1,0]
	v_pk_fma_f32 v[202:203], v[222:223], v[222:223], v[202:203]
	v_add_f32_e32 v149, v204, v205
	v_pk_mul_f32 v[218:219], v[24:25], v[198:199] op_sel_hi:[1,0]
	v_pk_mul_f32 v[200:201], v[220:221], v[220:221]
	v_add_f32_e32 v149, v202, v149
	v_pk_mul_f32 v[216:217], v[10:11], v[198:199] op_sel_hi:[1,0]
	v_pk_fma_f32 v[200:201], v[218:219], v[218:219], v[200:201]
	v_add_f32_e32 v149, v203, v149
	v_pk_mul_f32 v[214:215], v[26:27], v[198:199] op_sel_hi:[1,0]
	v_pk_mul_f32 v[198:199], v[216:217], v[216:217]
	v_add_f32_e32 v149, v200, v149
	v_pk_fma_f32 v[198:199], v[214:215], v[214:215], v[198:199]
	v_add_f32_e32 v149, v201, v149
	v_add_f32_e32 v149, v198, v149
	v_add_f32_e32 v149, v199, v149
	ds_bpermute_b32 v151, v167, v149
	ds_read_b128 v[198:201], v175
	ds_read_b128 v[202:205], v175 offset:16
	ds_read_b128 v[206:209], v175 offset:128
	ds_read_b128 v[210:213], v175 offset:144
	s_waitcnt lgkmcnt(4)
	v_add_f32_e32 v149, v149, v151
	ds_bpermute_b32 v151, v168, v149
	s_waitcnt lgkmcnt(0)
	v_add_f32_e32 v149, v149, v151
	v_fmamk_f32 v149, v149, 0x3c800000, v172
	v_mul_f32_e32 v151, 0x4b800000, v149
	v_cmp_gt_f32_e32 vcc, s39, v149
	s_nop 1
	v_cndmask_b32_e32 v149, v149, v151, vcc
	v_rsq_f32_e32 v149, v149
	s_nop 0
	v_mul_f32_e32 v151, 0x45800000, v149
	v_cndmask_b32_e32 v149, v149, v151, vcc
	v_mul_f32_e32 v230, v147, v149
	v_pk_mul_f32 v[228:229], v[228:229], v[230:231] op_sel_hi:[1,0]
	v_pk_mul_f32 v[224:225], v[224:225], v[230:231] op_sel_hi:[1,0]
	v_pk_mul_f32 v[214:215], v[214:215], v[230:231] op_sel_hi:[1,0]
	v_pk_mul_f32 v[226:227], v[226:227], v[230:231] op_sel_hi:[1,0]
	v_pk_mul_f32 v[222:223], v[222:223], v[230:231] op_sel_hi:[1,0]
	v_pk_mul_f32 v[218:219], v[218:219], v[230:231] op_sel_hi:[1,0]
	v_pk_mul_f32 v[216:217], v[216:217], v[230:231] op_sel_hi:[1,0]
	v_pk_mul_f32 v[206:207], v[206:207], v[228:229]
	v_pk_mul_f32 v[208:209], v[208:209], v[224:225]
	v_pk_mul_f32 v[204:205], v[204:205], v[214:215]
	v_pk_mul_f32 v[220:221], v[220:221], v[230:231] op_sel_hi:[1,0]
	v_pk_mul_f32 v[198:199], v[198:199], v[226:227]
	v_pk_mul_f32 v[200:201], v[200:201], v[222:223]
	v_pk_mul_f32 v[202:203], v[202:203], v[218:219]
	v_pk_mul_f32 v[212:213], v[212:213], v[216:217]
	v_pk_mul_f32 v[210:211], v[210:211], v[220:221]
	s_waitcnt vmcnt(3)
	v_mov_b32_e32 v214, v176
	v_mov_b32_e32 v215, v178
	v_mov_b32_e32 v178, v177
	s_waitcnt vmcnt(2)
	v_mov_b32_e32 v177, v182
	v_mov_b32_e32 v182, v181
	v_mov_b32_e32 v176, v180
	s_waitcnt vmcnt(1)
	v_mov_b32_e32 v181, v186
	v_mov_b32_e32 v186, v185
	s_waitcnt vmcnt(0)
	v_mov_b32_e32 v185, v190
	v_pk_mul_f32 v[216:217], v[178:179], v[206:207]
	v_pk_mul_f32 v[206:207], v[214:215], v[206:207]
	v_pk_mul_f32 v[218:219], v[182:183], v[208:209]
	v_mov_b32_e32 v190, v189
	v_mov_b32_e32 v180, v184
	v_mov_b32_e32 v184, v188
	v_pk_mul_f32 v[208:209], v[176:177], v[208:209]
	v_pk_fma_f32 v[214:215], v[214:215], v[198:199], v[216:217] neg_lo:[0,0,1] neg_hi:[0,0,1]
	v_pk_fma_f32 v[198:199], v[178:179], v[198:199], v[206:207]
	v_pk_fma_f32 v[178:179], v[176:177], v[200:201], v[218:219] neg_lo:[0,0,1] neg_hi:[0,0,1]
	v_pk_mul_f32 v[176:177], v[190:191], v[212:213]
	v_pk_mul_f32 v[220:221], v[186:187], v[210:211]
	v_pk_fma_f32 v[188:189], v[184:185], v[204:205], v[176:177] neg_lo:[0,0,1] neg_hi:[0,0,1]
	v_pk_mul_f32 v[176:177], v[184:185], v[212:213]
	v_pk_mul_f32 v[210:211], v[180:181], v[210:211]
	v_pk_fma_f32 v[182:183], v[182:183], v[200:201], v[208:209]
	v_pk_fma_f32 v[180:181], v[180:181], v[202:203], v[220:221] neg_lo:[0,0,1] neg_hi:[0,0,1]
	v_pk_fma_f32 v[184:185], v[190:191], v[204:205], v[176:177]
	v_cvt_pk_bf16_f32 v177, v178, v179
	v_cvt_pk_bf16_f32 v178, v180, v181
	v_cvt_pk_bf16_f32 v181, v182, v183
	v_cvt_pk_bf16_f32 v183, v184, v185
	v_mad_i64_i32 v[184:185], s[8:9], v192, s40, v[154:155]
	v_pk_fma_f32 v[186:187], v[186:187], v[202:203], v[210:211]
	v_cvt_pk_bf16_f32 v176, v214, v215
	v_cvt_pk_bf16_f32 v179, v188, v189
	v_lshl_add_u64 v[184:185], v[184:185], 0, v[156:157]
	v_cvt_pk_bf16_f32 v180, v198, v199
	v_cvt_pk_bf16_f32 v182, v186, v187
	global_store_dwordx4 v[184:185], v[176:179], off
	global_store_dwordx4 v[184:185], v[180:183], off offset:64
	v_add_u32_e32 v192, 0xb0, v146
	v_ashrrev_i32_e32 v193, 31, v192
	v_lshlrev_b64 v[176:177], 8, v[192:193]
	v_lshl_add_u64 v[188:189], v[136:137], 0, v[176:177]
	global_load_dwordx4 v[176:179], v[188:189], off
	global_load_dwordx4 v[180:183], v[188:189], off offset:16
	global_load_dwordx4 v[184:187], v[188:189], off offset:32
	s_nop 0
	global_load_dwordx4 v[188:191], v[188:189], off offset:48
	ds_read_b32 v198, v174 offset:704
	v_mad_i64_i32 v[154:155], s[8:9], v192, s40, v[154:155]
	v_lshl_add_u64 v[154:155], v[154:155], 0, v[156:157]
	s_waitcnt lgkmcnt(0)
	v_pk_mul_f32 v[228:229], v[4:5], v[198:199] op_sel_hi:[1,0]
	v_pk_mul_f32 v[224:225], v[6:7], v[198:199] op_sel_hi:[1,0]
	v_pk_mul_f32 v[226:227], v[20:21], v[198:199] op_sel_hi:[1,0]
	v_pk_mul_f32 v[204:205], v[228:229], v[228:229]
	v_pk_mul_f32 v[222:223], v[22:23], v[198:199] op_sel_hi:[1,0]
	v_pk_mul_f32 v[202:203], v[224:225], v[224:225]
	v_pk_fma_f32 v[204:205], v[226:227], v[226:227], v[204:205]
	v_pk_mul_f32 v[220:221], v[0:1], v[198:199] op_sel_hi:[1,0]
	v_pk_fma_f32 v[202:203], v[222:223], v[222:223], v[202:203]
	v_add_f32_e32 v149, v204, v205
	v_pk_mul_f32 v[218:219], v[12:13], v[198:199] op_sel_hi:[1,0]
	v_pk_mul_f32 v[200:201], v[220:221], v[220:221]
	v_add_f32_e32 v149, v202, v149
	v_pk_mul_f32 v[216:217], v[2:3], v[198:199] op_sel_hi:[1,0]
	v_pk_fma_f32 v[200:201], v[218:219], v[218:219], v[200:201]
	v_add_f32_e32 v149, v203, v149
	v_pk_mul_f32 v[214:215], v[14:15], v[198:199] op_sel_hi:[1,0]
	v_pk_mul_f32 v[198:199], v[216:217], v[216:217]
	v_add_f32_e32 v149, v200, v149
	v_pk_fma_f32 v[198:199], v[214:215], v[214:215], v[198:199]
	v_add_f32_e32 v149, v201, v149
	v_add_f32_e32 v149, v198, v149
	v_add_f32_e32 v149, v199, v149
	ds_bpermute_b32 v151, v167, v149
	ds_read_b128 v[198:201], v175
	ds_read_b128 v[202:205], v175 offset:16
	ds_read_b128 v[206:209], v175 offset:128
	ds_read_b128 v[210:213], v175 offset:144
	s_waitcnt lgkmcnt(4)
	v_add_f32_e32 v149, v149, v151
	ds_bpermute_b32 v151, v168, v149
	s_waitcnt lgkmcnt(0)
	v_add_f32_e32 v149, v149, v151
	v_fmamk_f32 v149, v149, 0x3c800000, v172
	v_mul_f32_e32 v151, 0x4b800000, v149
	v_cmp_gt_f32_e32 vcc, s39, v149
	s_nop 1
	v_cndmask_b32_e32 v149, v149, v151, vcc
	v_rsq_f32_e32 v149, v149
	s_nop 0
	v_mul_f32_e32 v151, 0x45800000, v149
	v_cndmask_b32_e32 v149, v149, v151, vcc
	v_mul_f32_e32 v230, v147, v149
	v_pk_mul_f32 v[228:229], v[228:229], v[230:231] op_sel_hi:[1,0]
	v_pk_mul_f32 v[224:225], v[224:225], v[230:231] op_sel_hi:[1,0]
	v_pk_mul_f32 v[214:215], v[214:215], v[230:231] op_sel_hi:[1,0]
	v_pk_mul_f32 v[226:227], v[226:227], v[230:231] op_sel_hi:[1,0]
	v_pk_mul_f32 v[222:223], v[222:223], v[230:231] op_sel_hi:[1,0]
	v_pk_mul_f32 v[218:219], v[218:219], v[230:231] op_sel_hi:[1,0]
	v_pk_mul_f32 v[220:221], v[220:221], v[230:231] op_sel_hi:[1,0]
	v_pk_mul_f32 v[216:217], v[216:217], v[230:231] op_sel_hi:[1,0]
	v_pk_mul_f32 v[206:207], v[206:207], v[228:229]
	v_pk_mul_f32 v[208:209], v[208:209], v[224:225]
	v_pk_mul_f32 v[204:205], v[204:205], v[214:215]
	v_pk_mul_f32 v[198:199], v[198:199], v[226:227]
	v_pk_mul_f32 v[200:201], v[200:201], v[222:223]
	v_pk_mul_f32 v[202:203], v[202:203], v[218:219]
	v_pk_mul_f32 v[210:211], v[210:211], v[220:221]
	v_pk_mul_f32 v[212:213], v[212:213], v[216:217]
	s_waitcnt vmcnt(3)
	v_mov_b32_e32 v214, v176
	v_mov_b32_e32 v215, v178
	v_mov_b32_e32 v178, v177
	s_waitcnt vmcnt(2)
	v_mov_b32_e32 v177, v182
	v_mov_b32_e32 v182, v181
	v_mov_b32_e32 v176, v180
	s_waitcnt vmcnt(1)
	v_mov_b32_e32 v181, v186
	v_mov_b32_e32 v186, v185
	s_waitcnt vmcnt(0)
	v_mov_b32_e32 v185, v190
	v_pk_mul_f32 v[216:217], v[178:179], v[206:207]
	v_pk_mul_f32 v[206:207], v[214:215], v[206:207]
	v_pk_mul_f32 v[218:219], v[182:183], v[208:209]
	v_mov_b32_e32 v190, v189
	v_mov_b32_e32 v180, v184
	v_mov_b32_e32 v184, v188
	v_pk_mul_f32 v[208:209], v[176:177], v[208:209]
	v_pk_mul_f32 v[220:221], v[186:187], v[210:211]
	v_pk_fma_f32 v[214:215], v[214:215], v[198:199], v[216:217] neg_lo:[0,0,1] neg_hi:[0,0,1]
	v_pk_fma_f32 v[198:199], v[178:179], v[198:199], v[206:207]
	v_pk_fma_f32 v[178:179], v[176:177], v[200:201], v[218:219] neg_lo:[0,0,1] neg_hi:[0,0,1]
	v_pk_mul_f32 v[176:177], v[190:191], v[212:213]
	v_pk_mul_f32 v[210:211], v[180:181], v[210:211]
	v_pk_fma_f32 v[180:181], v[180:181], v[202:203], v[220:221] neg_lo:[0,0,1] neg_hi:[0,0,1]
	v_pk_fma_f32 v[188:189], v[184:185], v[204:205], v[176:177] neg_lo:[0,0,1] neg_hi:[0,0,1]
	v_pk_mul_f32 v[176:177], v[184:185], v[212:213]
	v_pk_fma_f32 v[182:183], v[182:183], v[200:201], v[208:209]
	v_pk_fma_f32 v[186:187], v[186:187], v[202:203], v[210:211]
	v_pk_fma_f32 v[184:185], v[190:191], v[204:205], v[176:177]
	v_cvt_pk_bf16_f32 v176, v214, v215
	v_cvt_pk_bf16_f32 v177, v178, v179
	v_cvt_pk_bf16_f32 v178, v180, v181
	v_cvt_pk_bf16_f32 v179, v188, v189
	v_cvt_pk_bf16_f32 v180, v198, v199
	v_cvt_pk_bf16_f32 v181, v182, v183
	v_cvt_pk_bf16_f32 v182, v186, v187
	v_cvt_pk_bf16_f32 v183, v184, v185
	global_store_dwordx4 v[154:155], v[176:179], off
	global_store_dwordx4 v[154:155], v[180:183], off offset:64
	s_cbranch_execnz .LBB0_943
.LBB0_945:
	ds_read2_b32 v[176:177], v174 offset1:16
	v_lshl_add_u32 v156, s46, 8, v164
	v_ashrrev_i32_e32 v157, 31, v156
	v_mov_b64_e32 v[154:155], s[96:97]
	s_and_b32 s24, s2, 7
	s_lshl_b32 s24, s24, 22
	s_add_u32 s24, s24, 0x2000000
	v_mov_b32_e32 v236, s24
	v_mov_b32_e32 v237, 0
	v_lshl_add_u64 v[154:155], v[154:155], 0, v[236:237]
	v_mad_i64_i32 v[178:179], s[8:9], v146, s40, v[154:155]
	v_lshlrev_b64 v[156:157], 1, v[156:157]
	s_waitcnt lgkmcnt(0)
	v_pk_mul_f32 v[126:127], v[126:127], v[176:177] op_sel_hi:[1,0]
	v_pk_mul_f32 v[124:125], v[124:125], v[176:177] op_sel_hi:[1,0]
	v_pk_mul_f32 v[180:181], v[122:123], v[176:177] op_sel_hi:[1,0]
	v_pk_mul_f32 v[122:123], v[120:121], v[176:177] op_sel_hi:[1,0]
	v_lshl_add_u64 v[178:179], v[178:179], 0, v[156:157]
	v_cvt_pk_bf16_f32 v120, v124, v125
	v_cvt_pk_bf16_f32 v121, v126, v127
	v_cvt_pk_bf16_f32 v122, v122, v123
	v_cvt_pk_bf16_f32 v123, v180, v181
	global_store_dwordx4 v[178:179], v[120:123], off
	v_pk_mul_f32 v[114:115], v[114:115], v[176:177] op_sel_hi:[1,0]
	v_pk_mul_f32 v[112:113], v[112:113], v[176:177] op_sel_hi:[1,0]
	v_pk_mul_f32 v[120:121], v[106:107], v[176:177] op_sel_hi:[1,0]
	v_pk_mul_f32 v[106:107], v[104:105], v[176:177] op_sel_hi:[1,0]
	v_cvt_pk_bf16_f32 v104, v112, v113
	v_cvt_pk_bf16_f32 v105, v114, v115
	v_cvt_pk_bf16_f32 v106, v106, v107
	v_cvt_pk_bf16_f32 v107, v120, v121
	global_store_dwordx4 v[178:179], v[104:107], off offset:256
	v_mov_b32_e32 v114, v177
	v_pk_mul_f32 v[110:111], v[110:111], v[114:115] op_sel_hi:[1,0]
	v_mad_i64_i32 v[104:105], s[8:9], v152, s40, v[154:155]
	v_lshl_add_u64 v[112:113], v[104:105], 0, v[156:157]
	v_pk_mul_f32 v[106:107], v[118:119], v[114:115] op_sel_hi:[1,0]
	v_pk_mul_f32 v[104:105], v[116:117], v[114:115] op_sel_hi:[1,0]
	v_pk_mul_f32 v[108:109], v[108:109], v[114:115] op_sel_hi:[1,0]
	v_cvt_pk_bf16_f32 v104, v104, v105
	v_cvt_pk_bf16_f32 v105, v106, v107
	v_cvt_pk_bf16_f32 v106, v108, v109
	v_cvt_pk_bf16_f32 v107, v110, v111
	v_pk_mul_f32 v[96:97], v[96:97], v[114:115] op_sel_hi:[1,0]
	global_store_dwordx4 v[112:113], v[104:107], off
	v_pk_mul_f32 v[98:99], v[98:99], v[114:115] op_sel_hi:[1,0]
	s_nop 0
	v_pk_mul_f32 v[104:105], v[90:91], v[114:115] op_sel_hi:[1,0]
	v_pk_mul_f32 v[90:91], v[88:89], v[114:115] op_sel_hi:[1,0]
	v_cvt_pk_bf16_f32 v88, v96, v97
	ds_read2_b32 v[96:97], v174 offset0:32 offset1:48
	v_cvt_pk_bf16_f32 v89, v98, v99
	v_cvt_pk_bf16_f32 v90, v90, v91
	v_cvt_pk_bf16_f32 v91, v104, v105
	global_store_dwordx4 v[112:113], v[88:91], off offset:256
	s_waitcnt lgkmcnt(0)
	v_pk_mul_f32 v[94:95], v[94:95], v[96:97] op_sel_hi:[1,0]
	v_pk_mul_f32 v[92:93], v[92:93], v[96:97] op_sel_hi:[1,0]
	v_mad_i64_i32 v[88:89], s[8:9], v150, s40, v[154:155]
	v_lshl_add_u64 v[98:99], v[88:89], 0, v[156:157]
	v_pk_mul_f32 v[90:91], v[102:103], v[96:97] op_sel_hi:[1,0]
	v_pk_mul_f32 v[88:89], v[100:101], v[96:97] op_sel_hi:[1,0]
	v_pk_mul_f32 v[82:83], v[82:83], v[96:97] op_sel_hi:[1,0]
	v_cvt_pk_bf16_f32 v88, v88, v89
	v_cvt_pk_bf16_f32 v89, v90, v91
	v_cvt_pk_bf16_f32 v90, v92, v93
	v_cvt_pk_bf16_f32 v91, v94, v95
	global_store_dwordx4 v[98:99], v[88:91], off
	v_pk_mul_f32 v[80:81], v[80:81], v[96:97] op_sel_hi:[1,0]
	s_nop 0
	v_pk_mul_f32 v[88:89], v[74:75], v[96:97] op_sel_hi:[1,0]
	v_pk_mul_f32 v[74:75], v[72:73], v[96:97] op_sel_hi:[1,0]
	v_cvt_pk_bf16_f32 v72, v80, v81
	v_cvt_pk_bf16_f32 v73, v82, v83
	v_cvt_pk_bf16_f32 v74, v74, v75
	v_cvt_pk_bf16_f32 v75, v88, v89
	global_store_dwordx4 v[98:99], v[72:75], off offset:256
	v_mov_b32_e32 v82, v97
	v_pk_mul_f32 v[78:79], v[78:79], v[82:83] op_sel_hi:[1,0]
	v_mad_i64_i32 v[72:73], s[8:9], v148, s40, v[154:155]
	v_lshl_add_u64 v[80:81], v[72:73], 0, v[156:157]
	v_pk_mul_f32 v[74:75], v[86:87], v[82:83] op_sel_hi:[1,0]
	v_pk_mul_f32 v[72:73], v[84:85], v[82:83] op_sel_hi:[1,0]
	v_pk_mul_f32 v[76:77], v[76:77], v[82:83] op_sel_hi:[1,0]
	v_cvt_pk_bf16_f32 v72, v72, v73
	v_cvt_pk_bf16_f32 v73, v74, v75
	v_cvt_pk_bf16_f32 v74, v76, v77
	v_cvt_pk_bf16_f32 v75, v78, v79
	global_store_dwordx4 v[80:81], v[72:75], off
	v_pk_mul_f32 v[70:71], v[70:71], v[82:83] op_sel_hi:[1,0]
	v_pk_mul_f32 v[68:69], v[68:69], v[82:83] op_sel_hi:[1,0]
	v_pk_mul_f32 v[72:73], v[66:67], v[82:83] op_sel_hi:[1,0]
	v_pk_mul_f32 v[66:67], v[64:65], v[82:83] op_sel_hi:[1,0]
	v_cvt_pk_bf16_f32 v64, v68, v69
	v_cvt_pk_bf16_f32 v65, v70, v71
	v_cvt_pk_bf16_f32 v66, v66, v67
	v_cvt_pk_bf16_f32 v67, v72, v73
	global_store_dwordx4 v[80:81], v[64:67], off offset:256
	ds_read2_b32 v[64:65], v174 offset0:128 offset1:144
	s_waitcnt lgkmcnt(0)
	v_pk_mul_f32 v[62:63], v[62:63], v[64:65] op_sel_hi:[1,0]
	v_add_u32_e32 v66, 0x80, v146
	v_mad_i64_i32 v[66:67], s[8:9], v66, s40, v[154:155]
	v_pk_mul_f32 v[60:61], v[60:61], v[64:65] op_sel_hi:[1,0]
	v_pk_mul_f32 v[68:69], v[58:59], v[64:65] op_sel_hi:[1,0]
	v_pk_mul_f32 v[58:59], v[56:57], v[64:65] op_sel_hi:[1,0]
	v_lshl_add_u64 v[66:67], v[66:67], 0, v[156:157]
	v_cvt_pk_bf16_f32 v56, v60, v61
	v_cvt_pk_bf16_f32 v57, v62, v63
	v_cvt_pk_bf16_f32 v58, v58, v59
	v_cvt_pk_bf16_f32 v59, v68, v69
	global_store_dwordx4 v[66:67], v[56:59], off
	v_pk_mul_f32 v[50:51], v[50:51], v[64:65] op_sel_hi:[1,0]
	v_pk_mul_f32 v[48:49], v[48:49], v[64:65] op_sel_hi:[1,0]
	v_pk_mul_f32 v[56:57], v[42:43], v[64:65] op_sel_hi:[1,0]
	v_pk_mul_f32 v[42:43], v[40:41], v[64:65] op_sel_hi:[1,0]
	v_cvt_pk_bf16_f32 v40, v48, v49
	v_cvt_pk_bf16_f32 v41, v50, v51
	v_cvt_pk_bf16_f32 v42, v42, v43
	v_cvt_pk_bf16_f32 v43, v56, v57
	global_store_dwordx4 v[66:67], v[40:43], off offset:256
	v_mov_b32_e32 v50, v65
	v_pk_mul_f32 v[46:47], v[46:47], v[50:51] op_sel_hi:[1,0]
	v_add_u32_e32 v40, 0x90, v146
	v_mad_i64_i32 v[40:41], s[8:9], v40, s40, v[154:155]
	v_lshl_add_u64 v[48:49], v[40:41], 0, v[156:157]
	v_pk_mul_f32 v[42:43], v[54:55], v[50:51] op_sel_hi:[1,0]
	v_pk_mul_f32 v[40:41], v[52:53], v[50:51] op_sel_hi:[1,0]
	v_pk_mul_f32 v[44:45], v[44:45], v[50:51] op_sel_hi:[1,0]
	v_cvt_pk_bf16_f32 v40, v40, v41
	v_cvt_pk_bf16_f32 v41, v42, v43
	v_cvt_pk_bf16_f32 v42, v44, v45
	v_cvt_pk_bf16_f32 v43, v46, v47
	global_store_dwordx4 v[48:49], v[40:43], off
	v_pk_mul_f32 v[38:39], v[38:39], v[50:51] op_sel_hi:[1,0]
	v_pk_mul_f32 v[36:37], v[36:37], v[50:51] op_sel_hi:[1,0]
	v_pk_mul_f32 v[40:41], v[30:31], v[50:51] op_sel_hi:[1,0]
	v_pk_mul_f32 v[30:31], v[28:29], v[50:51] op_sel_hi:[1,0]
	v_cvt_pk_bf16_f32 v28, v36, v37
	v_cvt_pk_bf16_f32 v29, v38, v39
	v_cvt_pk_bf16_f32 v30, v30, v31
	v_cvt_pk_bf16_f32 v31, v40, v41
	global_store_dwordx4 v[48:49], v[28:31], off offset:256
	ds_read2_b32 v[28:29], v174 offset0:160 offset1:176
	s_waitcnt lgkmcnt(0)
	v_pk_mul_f32 v[34:35], v[34:35], v[28:29] op_sel_hi:[1,0]
	v_add_u32_e32 v30, 0xa0, v146
	v_mad_i64_i32 v[30:31], s[8:9], v30, s40, v[154:155]
	v_pk_mul_f32 v[32:33], v[32:33], v[28:29] op_sel_hi:[1,0]
	v_pk_mul_f32 v[36:37], v[26:27], v[28:29] op_sel_hi:[1,0]
	v_pk_mul_f32 v[26:27], v[24:25], v[28:29] op_sel_hi:[1,0]
	v_lshl_add_u64 v[30:31], v[30:31], 0, v[156:157]
	v_cvt_pk_bf16_f32 v24, v32, v33
	v_cvt_pk_bf16_f32 v25, v34, v35
	v_cvt_pk_bf16_f32 v26, v26, v27
	v_cvt_pk_bf16_f32 v27, v36, v37
	global_store_dwordx4 v[30:31], v[24:27], off
	v_pk_mul_f32 v[18:19], v[18:19], v[28:29] op_sel_hi:[1,0]
	v_pk_mul_f32 v[16:17], v[16:17], v[28:29] op_sel_hi:[1,0]
	v_pk_mul_f32 v[24:25], v[10:11], v[28:29] op_sel_hi:[1,0]
	v_pk_mul_f32 v[10:11], v[8:9], v[28:29] op_sel_hi:[1,0]
	v_cvt_pk_bf16_f32 v8, v16, v17
	v_cvt_pk_bf16_f32 v9, v18, v19
	v_cvt_pk_bf16_f32 v10, v10, v11
	v_cvt_pk_bf16_f32 v11, v24, v25
	global_store_dwordx4 v[30:31], v[8:11], off offset:256
	v_mov_b32_e32 v18, v29
	v_pk_mul_f32 v[14:15], v[14:15], v[18:19] op_sel_hi:[1,0]
	v_add_u32_e32 v8, 0xb0, v146
	v_mad_i64_i32 v[8:9], s[8:9], v8, s40, v[154:155]
	v_lshl_add_u64 v[16:17], v[8:9], 0, v[156:157]
	v_pk_mul_f32 v[10:11], v[22:23], v[18:19] op_sel_hi:[1,0]
	v_pk_mul_f32 v[8:9], v[20:21], v[18:19] op_sel_hi:[1,0]
	v_pk_mul_f32 v[12:13], v[12:13], v[18:19] op_sel_hi:[1,0]
	v_cvt_pk_bf16_f32 v8, v8, v9
	v_cvt_pk_bf16_f32 v9, v10, v11
	v_cvt_pk_bf16_f32 v10, v12, v13
	v_cvt_pk_bf16_f32 v11, v14, v15
	global_store_dwordx4 v[16:17], v[8:11], off
	v_pk_mul_f32 v[6:7], v[6:7], v[18:19] op_sel_hi:[1,0]
	v_pk_mul_f32 v[4:5], v[4:5], v[18:19] op_sel_hi:[1,0]
	v_pk_mul_f32 v[8:9], v[2:3], v[18:19] op_sel_hi:[1,0]
	v_pk_mul_f32 v[2:3], v[0:1], v[18:19] op_sel_hi:[1,0]
	v_cvt_pk_bf16_f32 v0, v4, v5
	v_cvt_pk_bf16_f32 v1, v6, v7
	v_cvt_pk_bf16_f32 v2, v2, v3
	v_cvt_pk_bf16_f32 v3, v8, v9
	global_store_dwordx4 v[16:17], v[0:3], off offset:256
	s_andn2_b64 vcc, exec, s[44:45]
	s_mov_b64 s[8:9], -1
	s_cbranch_vccnz .LBB0_934

.LBB0_1005:
	v_readlane_b32 s0, v241, 12
	s_and_b32 s3, s72, 0x380
	s_ashr_i32 s6, s0, 5
	s_lshl_b32 s0, s3, 1
	s_add_u32 s4, s90, s0
	s_addc_u32 s5, s91, 0
	s_lshl_b32 s12, s6, 22
	s_add_u32 s4, s4, s12
	s_addc_u32 s5, s5, 0
	s_xor_b32 s17, s57, 7
	s_add_u32 s33, s92, 0x3001000
	s_addc_u32 s52, s93, 0
	s_add_u32 s12, s12, 0x2000000
	s_add_u32 s33, s33, s12
	s_addc_u32 s52, s52, 0
	s_add_u32 s8, s92, s0
	s_addc_u32 s9, s93, 0
	s_ashr_i32 s7, s6, 31
	s_lshl_b64 s[0:1], s[6:7], 11
	s_mul_hi_i32 s7, s6, 0x1000000
	s_mul_i32 s6, s6, 0x1000000
	s_add_u32 s6, s6, 0x2000000
	s_addc_u32 s7, s7, 0
	s_add_u32 s53, s96, s6
	s_addc_u32 s55, s97, s7
	v_add_f32_e32 v0, v2, v3
	s_add_u32 s6, s8, s6
	s_mov_b32 s8, 0x3fb8aa3b
	v_mul_f32_e32 v1, 0x3fb8aa3b, v0
	v_fma_f32 v2, v0, s8, -v1
	v_rndne_f32_e32 v3, v1
	v_fmac_f32_e32 v2, 0x32a5705f, v0
	v_sub_f32_e32 v1, v1, v3
	v_add_f32_e32 v1, v1, v2
	v_exp_f32_e32 v1, v1
	v_cvt_i32_f32_e32 v2, v3
	s_waitcnt lgkmcnt(0)
	v_add_f32_e32 v3, v4, v5
	s_addc_u32 s7, s9, s7
	s_add_u32 s58, s6, 0x3000800
	v_ldexp_f32 v1, v1, v2
	v_mul_f32_e32 v2, 0x3fb8aa3b, v3
	v_fma_f32 v4, v3, s8, -v2
	v_rndne_f32_e32 v5, v2
	v_fmac_f32_e32 v4, 0x32a5705f, v3
	v_sub_f32_e32 v2, v2, v5
	v_add_f32_e32 v2, v2, v4
	v_exp_f32_e32 v2, v2
	v_cvt_i32_f32_e32 v4, v5
	s_mov_b32 s6, 0xc2ce8ed0
	s_addc_u32 s59, s7, 0
	v_cmp_ngt_f32_e32 vcc, s6, v0
	s_mov_b32 s7, 0x42b17218
	v_mov_b32_e32 v5, 0x7f800000
	v_cndmask_b32_e32 v1, 0, v1, vcc
	v_cmp_nlt_f32_e32 vcc, s7, v0
	s_mov_b32 s14, 0xfffa0000
	s_mov_b64 s[8:9], -1
	v_cndmask_b32_e32 v0, v5, v1, vcc
	v_ldexp_f32 v1, v2, v4
	v_cmp_ngt_f32_e32 vcc, s6, v3
	v_mov_b32_e32 v201, s77
	s_movk_i32 s60, 0x1800
	v_cndmask_b32_e32 v1, 0, v1, vcc
	v_cmp_nlt_f32_e32 vcc, s7, v3
	v_mov_b32_e32 v189, 0
	s_mov_b64 s[6:7], 0x60000
	v_cndmask_b32_e32 v1, v5, v1, vcc
	v_sub_f32_e32 v0, v0, v1
	v_add_f32_e32 v200, 0x3eb60549, v0
	s_mov_b64 s[10:11], 0xc0000
	s_mov_b64 s[12:13], 0x120000
	s_mov_b32 s15, -1
	s_mov_b32 s61, 0x41000000
	s_brev_b32 s16, 60
	s_mov_b32 s62, 0x800000
	v_mov_b32_e32 v202, 0xff800000
	v_mov_b32_e32 v203, 0x60000
	s_barrier
	s_branch .LBB0_1007

.LBB0_1213:
	s_add_u32 s0, s92, 0x300000
	s_addc_u32 s1, s93, 0
	s_and_b64 vcc, exec, s[42:43]
	s_cbranch_vccnz .LBB0_1249
	s_lshl_b32 s3, s77, 10
	v_lshlrev_b32_e32 v15, 4, v8
	v_add_u32_e32 v0, s3, v15
	v_ashrrev_i32_e32 v1, 31, v0
	v_lshrrev_b32_e32 v1, 22, v1
	v_add_u32_e32 v1, v0, v1
	v_ashrrev_i32_e32 v9, 10, v1
	v_mul_i32_i24_e32 v1, 0x400, v9
	v_sub_u32_e32 v1, v0, v1
	v_lshrrev_b32_e32 v2, 4, v1
	v_bitop3_b32 v1, v2, v1, 32 bitop3:0x6c
	v_ashrrev_i32_e32 v3, 31, v1
	v_lshrrev_b32_e32 v3, 26, v3
	v_add_u32_e32 v3, v1, v3
	v_lshlrev_b32_e32 v2, 3, v9
	v_ashrrev_i32_e32 v10, 6, v3
	v_and_b32_e32 v3, 0xc0, v3
	v_and_b32_e32 v2, -16, v2
	v_sub_u32_e32 v1, v1, v3
	v_mov_b32_e32 v3, 1
	v_add_u32_e32 v2, v10, v2
	v_ashrrev_i16_sdwa v1, v3, sext(v1) dst_sel:DWORD dst_unused:UNUSED_PAD src0_sel:DWORD src1_sel:BYTE_0
	v_lshlrev_b32_e32 v4, 5, v9
	v_bfe_i32 v11, v1, 0, 16
	v_lshlrev_b32_e32 v1, 1, v2
	v_lshrrev_b32_e32 v5, 2, v2
	v_and_b32_e32 v6, 3, v10
	s_mov_b32 s4, 0x1fffe0
	v_and_b32_e32 v4, 32, v4
	v_and_b32_e32 v1, 24, v1
	v_and_b32_e32 v5, 4, v5
	v_and_or_b32 v6, v2, s4, v6
	v_or3_b32 v1, v6, v5, v1
	v_add_lshl_u32 v4, v4, v11, 1
	v_add_u32_e32 v0, 0x2000, v0
	v_lshl_add_u32 v130, v1, 11, v4
	v_ashrrev_i32_e32 v1, 31, v0
	v_lshrrev_b32_e32 v1, 22, v1
	v_add_u32_e32 v1, v0, v1
	v_ashrrev_i32_e32 v12, 10, v1
	v_mul_i32_i24_e32 v1, 0x400, v12
	v_sub_u32_e32 v0, v0, v1
	v_lshrrev_b32_e32 v1, 4, v0
	v_bitop3_b32 v0, v1, v0, 32 bitop3:0x6c
	v_lshl_add_u32 v128, v2, 11, v4
	v_ashrrev_i32_e32 v2, 31, v0
	v_lshrrev_b32_e32 v2, 26, v2
	v_add_u32_e32 v2, v0, v2
	v_ashrrev_i32_e32 v13, 6, v2
	v_and_b32_e32 v2, 0xffc0, v2
	v_sub_u32_e32 v0, v0, v2
	v_lshrrev_b16_e32 v2, 7, v0
	v_lshlrev_b32_e32 v1, 3, v12
	v_and_b32_e32 v2, 1, v2
	v_and_b32_e32 v1, -16, v1
	v_add_u16_e32 v0, v0, v2
	v_add_u32_e32 v1, v13, v1
	v_ashrrev_i16_sdwa v0, v3, sext(v0) dst_sel:DWORD dst_unused:UNUSED_PAD src0_sel:DWORD src1_sel:BYTE_0
	v_and_b32_e32 v3, 3, v13
	s_ashr_i32 s27, s26, 31
	s_ashr_i32 s7, s6, 31
	s_ashr_i32 s12, s77, 2
	v_and_or_b32 v3, v1, s4, v3
	s_lshl_b64 s[10:11], s[26:27], 19
	s_lshl_b64 s[4:5], s[6:7], 19
	s_add_u32 s8, s50, s4
	v_lshlrev_b32_e32 v4, 5, v12
	v_bfe_i32 v14, v0, 0, 16
	v_lshlrev_b32_e32 v0, 1, v1
	v_lshrrev_b32_e32 v2, 2, v1
	s_addc_u32 s9, s51, s5
	s_add_i32 s4, s3, 0
	v_and_b32_e32 v4, 32, v4
	v_and_b32_e32 v0, 24, v0
	v_and_b32_e32 v2, 4, v2
	s_add_i32 m0, s4, 0x10000
	v_or3_b32 v0, v3, v2, v0
	v_add_lshl_u32 v2, v4, v14, 1
	global_load_lds_dwordx4 v130, s[8:9]
	s_add_i32 m0, s4, 0x12000
	v_lshl_add_u32 v134, v0, 11, v2
	s_add_u32 s14, s8, 0x40000
	global_load_lds_dwordx4 v134, s[8:9]
	s_addc_u32 s15, s9, 0
	s_add_i32 m0, s4, 0x14000
	v_lshl_add_u32 v132, v1, 11, v2
	global_load_lds_dwordx4 v130, s[14:15]
	s_add_i32 m0, s4, 0x16000
	s_add_u32 s28, s90, s10
	s_addc_u32 s29, s91, s11
	s_and_b32 s21, s2, 7
	s_lshl_b32 s21, s21, 22
	s_add_u32 s28, s28, s21
	s_addc_u32 s29, s29, 0
	s_add_i32 s5, s4, 0x2000
	global_load_lds_dwordx4 v134, s[14:15]
	s_mov_b32 m0, s4
	s_add_u32 s10, s28, 0x40000
	global_load_lds_dwordx4 v128, s[28:29]
	s_mov_b32 m0, s5
	s_addc_u32 s11, s29, 0
	s_add_i32 s33, s4, 0x4000
	global_load_lds_dwordx4 v132, s[28:29]
	s_mov_b32 m0, s33
	s_add_i32 s36, s4, 0x6000
	global_load_lds_dwordx4 v128, s[10:11]
	s_mov_b32 m0, s36
	v_mov_b32_e32 v131, 0
	global_load_lds_dwordx4 v132, s[10:11]
	v_mov_b32_e32 v135, v131
	v_mov_b32_e32 v129, v131
	v_mov_b32_e32 v133, v131
	s_cmp_eq_u32 s12, 1
	s_mov_b32 s7, 0
	v_lshl_add_u64 v[6:7], s[8:9], 0, v[130:131]
	v_lshl_add_u64 v[4:5], s[8:9], 0, v[134:135]
	v_lshl_add_u64 v[0:1], s[28:29], 0, v[128:129]
	s_cselect_b64 s[10:11], -1, 0
	s_cmp_lg_u32 s12, 1
	v_lshl_add_u64 v[2:3], s[28:29], 0, v[132:133]
	s_cbranch_scc1 .LBB0_1216
	s_barrier

.LBB0_1225:
	s_ashr_i32 s21, s20, 31
	s_lshl_b64 s[22:23], s[20:21], 19
	s_add_u32 s22, s90, s22
	s_addc_u32 s23, s91, s23
	s_and_b32 s21, s2, 7
	s_lshl_b32 s21, s21, 22
	s_add_u32 s22, s22, s21
	s_addc_u32 s23, s23, 0
	s_and_b64 s[24:25], s[46:47], exec
	s_cselect_b32 s21, s23, s29
	s_cselect_b32 s27, s22, s28
	s_ashr_i32 s17, s16, 31
	s_lshl_b64 s[24:25], s[16:17], 19
	s_add_u32 s24, s50, s24
	s_addc_u32 s25, s51, s25
	s_and_b64 s[30:31], s[46:47], exec
	s_cselect_b32 s17, s25, s9
	s_cselect_b32 s53, s24, s8
	s_add_u32 s28, s28, 0x40080
	s_addc_u32 s29, s29, 0
	s_add_u32 s55, s8, 0x100
	v_mov_b32_e32 v0, 0
	s_addc_u32 s57, s9, 0
	s_mov_b32 s58, -2
	s_waitcnt lgkmcnt(0)
	v_mov_b32_e32 v1, v0
	v_mov_b32_e32 v2, v0
	v_mov_b32_e32 v3, v0
	v_mov_b32_e32 v4, v0
	v_mov_b32_e32 v5, v0
	v_mov_b32_e32 v6, v0
	v_mov_b32_e32 v7, v0
	v_mov_b32_e32 v16, v0
	v_mov_b32_e32 v17, v0
	v_mov_b32_e32 v18, v0
	v_mov_b32_e32 v19, v0
	v_mov_b32_e32 v20, v0
	v_mov_b32_e32 v21, v0
	v_mov_b32_e32 v22, v0
	v_mov_b32_e32 v23, v0
	v_mov_b32_e32 v32, v0
	v_mov_b32_e32 v33, v0
	v_mov_b32_e32 v34, v0
	v_mov_b32_e32 v35, v0
	v_mov_b32_e32 v36, v0
	v_mov_b32_e32 v37, v0
	v_mov_b32_e32 v38, v0
	v_mov_b32_e32 v39, v0
	v_mov_b32_e32 v48, v0
	v_mov_b32_e32 v49, v0
	v_mov_b32_e32 v50, v0
	v_mov_b32_e32 v51, v0
	v_mov_b32_e32 v52, v0
	v_mov_b32_e32 v53, v0
	v_mov_b32_e32 v54, v0
	v_mov_b32_e32 v55, v0
	v_mov_b32_e32 v8, v0
	v_mov_b32_e32 v9, v0
	v_mov_b32_e32 v10, v0
	v_mov_b32_e32 v11, v0
	v_mov_b32_e32 v12, v0
	v_mov_b32_e32 v13, v0
	v_mov_b32_e32 v14, v0
	v_mov_b32_e32 v15, v0
	v_mov_b32_e32 v24, v0
	v_mov_b32_e32 v25, v0
	v_mov_b32_e32 v26, v0
	v_mov_b32_e32 v27, v0
	v_mov_b32_e32 v28, v0
	v_mov_b32_e32 v29, v0
	v_mov_b32_e32 v30, v0
	v_mov_b32_e32 v31, v0
	v_mov_b32_e32 v40, v0
	v_mov_b32_e32 v41, v0
	v_mov_b32_e32 v42, v0
	v_mov_b32_e32 v43, v0
	v_mov_b32_e32 v44, v0
	v_mov_b32_e32 v45, v0
	v_mov_b32_e32 v46, v0
	v_mov_b32_e32 v47, v0
	v_mov_b32_e32 v56, v0
	v_mov_b32_e32 v57, v0
	v_mov_b32_e32 v58, v0
	v_mov_b32_e32 v59, v0
	v_mov_b32_e32 v60, v0
	v_mov_b32_e32 v61, v0
	v_mov_b32_e32 v62, v0
	v_mov_b32_e32 v63, v0
	v_mov_b32_e32 v64, v0
	v_mov_b32_e32 v65, v0
	v_mov_b32_e32 v66, v0
	v_mov_b32_e32 v67, v0
	v_mov_b32_e32 v68, v0
	v_mov_b32_e32 v69, v0
	v_mov_b32_e32 v70, v0
	v_mov_b32_e32 v71, v0
	v_mov_b32_e32 v80, v0
	v_mov_b32_e32 v81, v0
	v_mov_b32_e32 v82, v0
	v_mov_b32_e32 v83, v0
	v_mov_b32_e32 v84, v0
	v_mov_b32_e32 v85, v0
	v_mov_b32_e32 v86, v0
	v_mov_b32_e32 v87, v0
	v_mov_b32_e32 v96, v0
	v_mov_b32_e32 v97, v0
	v_mov_b32_e32 v98, v0
	v_mov_b32_e32 v99, v0
	v_mov_b32_e32 v100, v0
	v_mov_b32_e32 v101, v0
	v_mov_b32_e32 v102, v0
	v_mov_b32_e32 v103, v0
	v_mov_b32_e32 v112, v0
	v_mov_b32_e32 v113, v0
	v_mov_b32_e32 v114, v0
	v_mov_b32_e32 v115, v0
	v_mov_b32_e32 v116, v0
	v_mov_b32_e32 v117, v0
	v_mov_b32_e32 v118, v0
	v_mov_b32_e32 v119, v0
	v_mov_b32_e32 v72, v0
	v_mov_b32_e32 v73, v0
	v_mov_b32_e32 v74, v0
	v_mov_b32_e32 v75, v0
	v_mov_b32_e32 v76, v0
	v_mov_b32_e32 v77, v0
	v_mov_b32_e32 v78, v0
	v_mov_b32_e32 v79, v0
	v_mov_b32_e32 v88, v0
	v_mov_b32_e32 v89, v0
	v_mov_b32_e32 v90, v0
	v_mov_b32_e32 v91, v0
	v_mov_b32_e32 v92, v0
	v_mov_b32_e32 v93, v0
	v_mov_b32_e32 v94, v0
	v_mov_b32_e32 v95, v0
	v_mov_b32_e32 v104, v0
	v_mov_b32_e32 v105, v0
	v_mov_b32_e32 v106, v0
	v_mov_b32_e32 v107, v0
	v_mov_b32_e32 v108, v0
	v_mov_b32_e32 v109, v0
	v_mov_b32_e32 v110, v0
	v_mov_b32_e32 v111, v0
	v_mov_b32_e32 v120, v0
	v_mov_b32_e32 v121, v0
	v_mov_b32_e32 v122, v0
	v_mov_b32_e32 v123, v0
	v_mov_b32_e32 v124, v0
	v_mov_b32_e32 v125, v0
	v_mov_b32_e32 v126, v0
	v_mov_b32_e32 v127, v0

.LBB0_1365:
	s_andn2_saveexec_b64 s[4:5], s[6:7]
	s_cbranch_execz .LBB0_1385
	v_mov_b32_e32 v1, 0x23ff8
	ds_read_b32 v1, v1
	s_waitcnt lgkmcnt(0)
	v_readfirstlane_b32 s3, v1
	s_nop 0
	s_cmp_lg_u32 s3, 0
	s_cbranch_scc1 .Lxloc_6
	s_mov_b64 s[6:7], exec
	buffer_wbl2 sc1
	s_waitcnt lgkmcnt(0)
	s_waitcnt vmcnt(0)
	v_mbcnt_lo_u32_b32 v1, s6, 0
	v_mbcnt_hi_u32_b32 v1, s7, v1
	v_cmp_eq_u32_e32 vcc, 0, v1
	s_and_saveexec_b64 s[8:9], vcc
	s_cbranch_execz .LBB0_1368
	s_bcnt1_i32_b64 s3, s[6:7]
	v_readlane_b32 s4, v240, 24
	v_mov_b32_e32 v2, 0
	v_mov_b32_e32 v3, s3
	v_readlane_b32 s5, v240, 25
	s_nop 4
	global_atomic_add v2, v2, v3, s[4:5] sc0
.LBB0_1368:
	s_or_b64 exec, exec, s[8:9]
	v_cvt_f32_u32_e32 v3, v0
	s_waitcnt vmcnt(0)
	v_readfirstlane_b32 s3, v2
	s_mov_b64 s[8:9], -1
	v_rcp_iflag_f32_e32 v3, v3
	v_add_u32_e32 v1, s3, v1
	v_add_u32_e32 v4, 1, v1
	v_mul_f32_e32 v2, 0x4f7ffffe, v3
	v_cvt_u32_f32_e32 v2, v2
	v_sub_u32_e32 v3, 0, v0
	v_mul_lo_u32 v3, v3, v2
	v_mul_hi_u32 v3, v2, v3
	v_add_u32_e32 v2, v2, v3
	v_mul_hi_u32 v2, v1, v2
	v_mul_lo_u32 v3, v2, v0
	v_sub_u32_e32 v1, v1, v3
	v_add_u32_e32 v5, 1, v2
	v_cmp_ge_u32_e32 vcc, v1, v0
	v_sub_u32_e32 v3, v1, v0
	s_nop 0
	v_cndmask_b32_e32 v2, v2, v5, vcc
	v_cndmask_b32_e32 v1, v1, v3, vcc
	v_add_u32_e32 v3, 1, v2
	v_cmp_ge_u32_e32 vcc, v1, v0
	s_nop 1
	v_cndmask_b32_e32 v2, v2, v3, vcc
	v_mul_lo_u32 v1, v0, v2
	v_add_u32_e32 v0, v1, v0
	v_cmp_ne_u32_e32 vcc, v4, v0
	v_mov_b64_e32 v[0:1], s[84:85]
	s_and_saveexec_b64 s[6:7], vcc
	s_cbranch_execz .LBB0_1380
	v_mov_b32_e32 v0, 0
	global_load_dword v1, v0, s[84:85] sc1
	s_mov_b64 s[10:11], 0
	s_waitcnt vmcnt(0)
	v_cmp_eq_u32_e32 vcc, v1, v2
	s_and_saveexec_b64 s[8:9], vcc
	s_cbranch_execz .LBB0_1379
	s_mov_b32 s3, 1
	s_branch .LBB0_1372
